# hand-written MLA attention block: LDS-DMA 5-buffer K/V tiles, two barriers per tile with wave groups one phase apart; plus MFMA finalize and scan re-mapping
# speedup vs baseline: 1.0185x; 1.0094x over previous
; #define LAS __attribute__((address_space(3)))
; template <int DQK, bool SWA>
; DI void attn_block(int wv, LAS unsigned char* lds, const bf16_t* Q, int ldq, int qoff, const bf16_t* K, int ldk, int koff, const bf16_t* Vt,
;                    int base, int T, int q0, bf16_t* O, int ldo, int ooff, const float* relb, int qhead, float sink_add) {
;     constexpr int KP = DQK * 2 + 16, CPR = DQK / 8, NKC = 64 * CPR, NKS = DQK / 16, KSZ = 13312;
;     const int tid = tid_(wv), lane = tid & 63, w = tid >> 6, r = lane & 31, h = lane >> 5;
;     LAS float* LUT = (LAS float*)(lds + ATT_LUT);
;     __syncthreads();
;     if (SWA) attn_lut(LUT, tid, relb, qhead);
;     const int qw0 = q0 + 32 * w, qpos = qw0 + r; const size_t qrow = (size_t)base + qpos;
;     bf16x8 qf[NKS];
; #pragma unroll
;     for (int ks = 0; ks < NKS; ++ks) qf[ks] = *(const bf16x8*)(Q + qrow * ldq + qoff + 16 * ks + 8 * h);
;     f32x16 o0, o1;
; #pragma unroll
;     for (int i = 0; i < 16; ++i) { o0[i] = 0.f; o1[i] = 0.f; }
;     float lsum = 0.f;
;     const int nt = (T + 63) >> 6;
;     int lo = 0, ntl = nt;
;     if (SWA) { lo = (q0 - 128) >> 6; if (lo < 1) lo = 1; int hi = (q0 + 255 + 128) >> 6; if (hi > nt - 1) hi = nt - 1; ntl = 1 + (hi >= lo ? hi - lo + 1 : 0); }
;     u32x4 kA0, kA1, vA, kB0, kB1, vB;
;     kA1 = (u32x4){0u, 0u, 0u, 0u}; kB1 = kA1;
;     const int kc0 = tid, kc1 = tid + 512;
;     const int kkey0 = kc0 / CPR, kpart0 = kc0 % CPR, kkey1 = kc1 / CPR, kpart1 = kc1 % CPR;
;     const int vd = tid >> 3, vpart = tid & 7;
; DI void phase_queue(int wv, const Params& p, int l, LAS unsigned char* lds) {
;     ...
;         if (it < N_MLA) {
;             int seq, head, qb;
;             if (it < 256) { seq = 0; head = it & 3; qb = it >> 2; } else { const int m = it - 256; seq = 1 + (m >> 5); head = m & 3; qb = (m >> 2) & 7; }
;             attn_block<96, false>(wv, lds, QM, 384, head * 96, KM, 384, head * 96, VTM + (size_t)head * 64 * MPAD, seq_start(seq), seq_len(seq), qb * 256, MIX, 1024, 768 + head * 64, nullptr, 0, 0.f);
.LBB0_1125:
	s_and_b64 vcc, exec, s[6:7]
	s_cbranch_vccz .LBB0_1170
	v_writelane_b32 v255, s4, 17
	v_writelane_b32 v255, s5, 18
	v_writelane_b32 v255, s6, 19
	v_writelane_b32 v255, s7, 20
	v_writelane_b32 v255, s8, 21
	v_writelane_b32 v255, s9, 22
	v_writelane_b32 v255, s10, 23
	v_writelane_b32 v255, s11, 24
	v_writelane_b32 v255, s12, 25
	v_writelane_b32 v255, s13, 26
	v_writelane_b32 v255, s14, 27
	v_writelane_b32 v255, s15, 28
	v_writelane_b32 v255, s16, 29
	v_writelane_b32 v255, s17, 30
	v_writelane_b32 v255, s18, 31
	v_writelane_b32 v255, s19, 32
	v_writelane_b32 v255, s20, 33
	v_writelane_b32 v255, s21, 34
	v_writelane_b32 v255, s22, 35
	v_writelane_b32 v255, s23, 36
	v_writelane_b32 v255, s24, 37
	v_writelane_b32 v255, s25, 38
	v_writelane_b32 v255, s26, 39
	v_writelane_b32 v255, s27, 40
	v_writelane_b32 v255, s28, 41
	v_writelane_b32 v255, s29, 42
	v_writelane_b32 v255, s30, 43
	v_writelane_b32 v255, s31, 44
	v_writelane_b32 v255, s36, 45
	v_writelane_b32 v255, s37, 46
	v_writelane_b32 v255, s38, 47
	v_writelane_b32 v255, s39, 48
	v_writelane_b32 v255, s40, 49
	v_writelane_b32 v255, s41, 50
	v_writelane_b32 v255, s42, 51
	v_writelane_b32 v255, s43, 52
	v_writelane_b32 v255, s44, 53
	v_writelane_b32 v255, s45, 54
	v_writelane_b32 v255, s46, 55
	v_writelane_b32 v255, s47, 56
	v_writelane_b32 v255, s48, 57
	v_writelane_b32 v255, s49, 58
	v_writelane_b32 v255, s50, 59
	v_writelane_b32 v255, s51, 60
	s_sub_u32 s4, s61, 0x294
	s_cmpk_lt_u32 s4, 0x100
	s_cbranch_scc1 .Lmlaa_seq0
	s_sub_u32 s5, s4, 0x100
	s_lshr_b32 s9, s5, 5
	s_add_u32 s9, s9, 1
	s_and_b32 s8, s5, 3
	s_bfe_u32 s10, s5, 0x30002
	s_mul_i32 s11, s9, 0x810
	s_add_u32 s11, s11, 0x3800
	s_movk_i32 s13, 33
	s_branch .Lmlaa_dec
.Lmlaa_seq0:
	s_mov_b32 s9, 0
	s_and_b32 s8, s4, 3
	s_lshr_b32 s10, s4, 2
	s_mov_b32 s11, 0
	s_movk_i32 s13, 0x101
.Lmlaa_dec:
	s_lshr_b32 s15, s33, 6
	s_mul_i32 s4, s8, 0xc0
	s_add_u32 s16, s34, 0x25f28000
	s_addc_u32 s17, s35, 0
	s_add_u32 s16, s16, s4
	s_addc_u32 s17, s17, 0
	s_mul_i32 s5, s11, 0x300
	s_add_u32 s18, s34, 0x29bb8000
	s_addc_u32 s19, s35, 0
	s_add_u32 s18, s18, s4
	s_addc_u32 s19, s19, 0
	s_add_u32 s18, s18, s5
	s_addc_u32 s19, s19, 0
	s_mul_i32 s4, s8, 0xa18000
	s_add_u32 s20, s34, 0x2d848000
	s_addc_u32 s21, s35, 0
	s_add_u32 s20, s20, s4
	s_addc_u32 s21, s21, 0
	s_lshl_b32 s4, s11, 1
	s_add_u32 s20, s20, s4
	s_addc_u32 s21, s21, 0
	s_lshl_b32 s4, s8, 7
	s_add_u32 s4, s4, 0x600
	s_add_u32 s22, s34, 0x19548000
	s_addc_u32 s23, s35, 0
	s_add_u32 s22, s22, s4
	s_addc_u32 s23, s23, 0
	v_and_b32_e32 v0, 31, v254
	v_lshrrev_b32_e32 v197, 5, v254
	v_mul_u32_u24_e32 v194, 0xd0, v0
	v_lshl_add_u32 v194, v197, 4, v194
	v_mul_u32_u24_e32 v195, 0x90, v0
	v_lshl_add_u32 v195, v197, 3, v195
	v_add_u32_e32 v195, 0x3400, v195
	v_add_u32_e32 v196, 0x1200, v195
	s_lshl_b32 s4, s10, 8
	s_add_u32 s4, s4, s11
	s_lshl_b32 s5, s15, 5
	s_add_u32 s4, s4, s5
	v_add_u32_e32 v198, s4, v0
	v_mul_u32_u24_e32 v199, 0x300, v198
	v_lshl_add_u32 v199, v197, 4, v199
	v_lshlrev_b32_e32 v198, 11, v198
	v_lshl_add_u32 v200, v197, 3, v198
	s_movk_i32 s48, 0x71c8
	s_movk_i32 s49, 0x4ec5
	s_mov_b32 s50, 0x28600
	s_movk_i32 s51, 0x300
	s_movk_i32 s28, 0x80
	s_mov_b32 s29, 0xc000
	s_add_u32 s4, s15, 0
	s_cmpk_gt_u32 s4, 12
	s_cselect_b32 s5, 9, 13
	s_cselect_b32 s6, s48, s49
	s_cselect_b32 s7, s50, s51
	s_cselect_b32 s36, s28, s29
	s_mov_b32 s37, 0
	s_cselect_b32 s44, s20, s18
	s_cselect_b32 s45, s21, s19
	s_cselect_b32 s46, 13, 0
	s_cselect_b32 s47, 0x3400, 0
	s_sub_u32 s4, s4, s46
	s_cmpk_gt_u32 s4, 8
	s_cselect_b32 s46, 9, 0
	s_cmpk_gt_u32 s47, 0
	s_cselect_b32 s46, s46, 0
	s_sub_u32 s4, s4, s46
	s_lshl_b32 s46, s4, 10
	s_add_u32 s24, s46, s47
	s_lshl_b32 s4, s4, 6
	v_add_u32_e32 v197, s4, v254
	v_mul_lo_u32 v198, v197, s6
	v_lshrrev_b32_e32 v198, 18, v198
	v_mul_lo_u32 v186, v198, s5
	v_sub_u32_e32 v197, v197, v186
	s_sub_u32 s4, s5, 1
	v_cmp_ne_u32_e32 vcc, s4, v197
	s_nop 1
	v_cndmask_b32_e32 v197, 0, v197, vcc
	v_mul_lo_u32 v198, v198, s7
	v_lshl_add_u32 v186, v197, 4, v198
	v_mov_b32_e32 v187, 0
	v_lshl_add_u64 v[186:187], s[44:45], 0, v[186:187]
	s_add_u32 s4, s15, 8
	s_cmpk_gt_u32 s4, 12
	s_cselect_b32 s5, 9, 13
	s_cselect_b32 s6, s48, s49
	s_cselect_b32 s7, s50, s51
	s_cselect_b32 s38, s28, s29
	s_mov_b32 s39, 0
	s_cselect_b32 s44, s20, s18
	s_cselect_b32 s45, s21, s19
	s_cselect_b32 s46, 13, 0
	s_cselect_b32 s47, 0x3400, 0
	s_sub_u32 s4, s4, s46
	s_cmpk_gt_u32 s4, 8
	s_cselect_b32 s46, 9, 0
	s_cmpk_gt_u32 s47, 0
	s_cselect_b32 s46, s46, 0
	s_sub_u32 s4, s4, s46
	s_lshl_b32 s46, s4, 10
	s_add_u32 s25, s46, s47
	s_lshl_b32 s4, s4, 6
	v_add_u32_e32 v197, s4, v254
	v_mul_lo_u32 v198, v197, s6
	v_lshrrev_b32_e32 v198, 18, v198
	v_mul_lo_u32 v188, v198, s5
	v_sub_u32_e32 v197, v197, v188
	s_sub_u32 s4, s5, 1
	v_cmp_ne_u32_e32 vcc, s4, v197
	s_nop 1
	v_cndmask_b32_e32 v197, 0, v197, vcc
	v_mul_lo_u32 v198, v198, s7
	v_lshl_add_u32 v188, v197, 4, v198
	v_mov_b32_e32 v189, 0
	v_lshl_add_u64 v[188:189], s[44:45], 0, v[188:189]
	s_add_u32 s4, s15, 16
	s_cmpk_gt_u32 s4, 12
	s_cselect_b32 s5, 9, 13
	s_cselect_b32 s6, s48, s49
	s_cselect_b32 s7, s50, s51
	s_cselect_b32 s40, s28, s29
	s_mov_b32 s41, 0
	s_cselect_b32 s44, s20, s18
	s_cselect_b32 s45, s21, s19
	s_cselect_b32 s46, 13, 0
	s_cselect_b32 s47, 0x3400, 0
	s_sub_u32 s4, s4, s46
	s_cmpk_gt_u32 s4, 8
	s_cselect_b32 s46, 9, 0
	s_cmpk_gt_u32 s47, 0
	s_cselect_b32 s46, s46, 0
	s_sub_u32 s4, s4, s46
	s_lshl_b32 s46, s4, 10
	s_add_u32 s26, s46, s47
	s_lshl_b32 s4, s4, 6
	v_add_u32_e32 v197, s4, v254
	v_mul_lo_u32 v198, v197, s6
	v_lshrrev_b32_e32 v198, 18, v198
	v_mul_lo_u32 v190, v198, s5
	v_sub_u32_e32 v197, v197, v190
; #define LAS __attribute__((address_space(3)))
; #define MFMA32(a, b, c) __builtin_amdgcn_mfma_f32_32x32x16_bf16((a), (b), (c), 0, 0, 0)
; #define ATT_GLOAD(k0_, k1_, v_, tile) do { const size_t rb = (size_t)base + (size_t)(tile) * 64; \
;         k0_ = *(const u32x4*)(K + (rb + kkey0) * ldk + koff + kpart0 * 8); \
;         if (kc1 < NKC) k1_ = *(const u32x4*)(K + (rb + kkey1) * ldk + koff + kpart1 * 8); \
;         v_ = *(const u32x4*)(Vt + (size_t)vd * MPAD + rb + vpart * 8); } while (0)
; template <int DQK, bool MASK>
; DI void attn_tile64(const bf16x8 (&qf)[DQK / 16], f32x16& o0, f32x16& o1, float& lsum, int kbase0, int r, int h, int T, const LAS unsigned char* Ksm, const LAS unsigned char* Vsm) {
;     constexpr int KP = DQK * 2 + 16, NKS = DQK / 16;
;     bf16x8 ka[2][NKS];
; #pragma unroll
;     for (int kt = 0; kt < 2; ++kt)
; #pragma unroll
;         for (int ks = 0; ks < NKS; ++ks) ka[kt][ks] = *(const LAS bf16x8*)(Ksm + (32 * kt + r) * KP + (16 * ks + 8 * h) * 2);
;     f32x16 sa[2];
; #pragma unroll
;     for (int kt = 0; kt < 2; ++kt)
; #pragma unroll
;         for (int i = 0; i < 16; ++i) sa[kt][i] = 0.f;
; #pragma unroll
;     for (int ks = 0; ks < NKS; ++ks)
; #pragma unroll
;         for (int kt = 0; kt < 2; ++kt) sa[kt] = MFMA32(ka[kt][ks], qf[ks], sa[kt]);
; template <int DQK, bool SWA>
; DI void attn_block(int wv, LAS unsigned char* lds, const bf16_t* Q, int ldq, int qoff, const bf16_t* K, int ldk, int koff, const bf16_t* Vt,
;                    int base, int T, int q0, bf16_t* O, int ldo, int ooff, const float* relb, int qhead, float sink_add) {
;     ...
;     ATT_GLOAD(kA0, kA1, vA, ATT_TILE(0)); ATT_LWRITE(kA0, kA1, vA, 0);
;     if (ntl > 1) ATT_GLOAD(kB0, kB1, vB, ATT_TILE(1));
;     if (ntl > 2) ATT_GLOAD(kA0, kA1, vA, ATT_TILE(2));
;     __syncthreads();
;     for (int it = 0; it < ntl; it += 2) {
;         if (it + 1 < ntl) ATT_LWRITE(kB0, kB1, vB, 1);
;         if (it + 3 < ntl) ATT_GLOAD(kB0, kB1, vB, ATT_TILE(it + 3));
;         ATT_COMPUTE(it);
;         __syncthreads();
;         if (it + 1 < ntl) {
;             if (it + 2 < ntl) ATT_LWRITE(kA0, kA1, vA, 0);
;             if (it + 4 < ntl) ATT_GLOAD(kA0, kA1, vA, ATT_TILE(it + 4));
;             ATT_COMPUTE(it + 1);
;             __syncthreads();
;         }
;     }
	s_sub_u32 s4, s5, 1
	v_cmp_ne_u32_e32 vcc, s4, v197
	s_nop 1
	v_cndmask_b32_e32 v197, 0, v197, vcc
	v_mul_lo_u32 v198, v198, s7
	v_lshl_add_u32 v190, v197, 4, v198
	v_mov_b32_e32 v191, 0
	v_lshl_add_u64 v[190:191], s[44:45], 0, v[190:191]
	global_load_dwordx4 v[2:5], v199, s[16:17] offset:0
	global_load_dwordx4 v[6:9], v199, s[16:17] offset:32
	global_load_dwordx4 v[10:13], v199, s[16:17] offset:64
	global_load_dwordx4 v[14:17], v199, s[16:17] offset:96
	global_load_dwordx4 v[18:21], v199, s[16:17] offset:128
	global_load_dwordx4 v[22:25], v199, s[16:17] offset:160
	s_mov_b32 s28, 0x0
	s_add_u32 m0, s28, s24
	s_nop 0
	global_load_lds_dwordx4 v[186:187], off
	v_lshl_add_u64 v[186:187], v[186:187], 0, s[36:37]
	s_add_u32 m0, s28, s25
	s_nop 0
	global_load_lds_dwordx4 v[188:189], off
	v_lshl_add_u64 v[188:189], v[188:189], 0, s[38:39]
	s_add_u32 m0, s28, s26
	s_nop 0
	global_load_lds_dwordx4 v[190:191], off
	v_lshl_add_u64 v[190:191], v[190:191], 0, s[40:41]
	s_mov_b32 s28, 0x5800
	s_add_u32 m0, s28, s24
	s_nop 0
	global_load_lds_dwordx4 v[186:187], off
	v_lshl_add_u64 v[186:187], v[186:187], 0, s[36:37]
	s_add_u32 m0, s28, s25
	s_nop 0
	global_load_lds_dwordx4 v[188:189], off
	v_lshl_add_u64 v[188:189], v[188:189], 0, s[38:39]
	s_add_u32 m0, s28, s26
	s_nop 0
	global_load_lds_dwordx4 v[190:191], off
	v_lshl_add_u64 v[190:191], v[190:191], 0, s[40:41]
	s_mov_b32 s28, 0xf000
	s_add_u32 m0, s28, s24
	s_nop 0
	global_load_lds_dwordx4 v[186:187], off
	v_lshl_add_u64 v[186:187], v[186:187], 0, s[36:37]
	s_add_u32 m0, s28, s25
	s_nop 0
	global_load_lds_dwordx4 v[188:189], off
	v_lshl_add_u64 v[188:189], v[188:189], 0, s[38:39]
	s_add_u32 m0, s28, s26
	s_nop 0
	global_load_lds_dwordx4 v[190:191], off
	v_lshl_add_u64 v[190:191], v[190:191], 0, s[40:41]
	s_mov_b32 s28, 0x14800
	s_add_u32 m0, s28, s24
	s_nop 0
	global_load_lds_dwordx4 v[186:187], off
	v_lshl_add_u64 v[186:187], v[186:187], 0, s[36:37]
	s_add_u32 m0, s28, s25
	s_nop 0
	global_load_lds_dwordx4 v[188:189], off
	v_lshl_add_u64 v[188:189], v[188:189], 0, s[38:39]
	s_add_u32 m0, s28, s26
	s_nop 0
	global_load_lds_dwordx4 v[190:191], off
	v_lshl_add_u64 v[190:191], v[190:191], 0, s[40:41]
	v_mov_b32_e32 v26, 0
	v_mov_b32_e32 v27, 0
	v_mov_b32_e32 v28, 0
	v_mov_b32_e32 v29, 0
	v_mov_b32_e32 v30, 0
	v_mov_b32_e32 v31, 0
	v_mov_b32_e32 v32, 0
	v_mov_b32_e32 v33, 0
	v_mov_b32_e32 v34, 0
	v_mov_b32_e32 v35, 0
	v_mov_b32_e32 v36, 0
	v_mov_b32_e32 v37, 0
	v_mov_b32_e32 v38, 0
	v_mov_b32_e32 v39, 0
	v_mov_b32_e32 v40, 0
	v_mov_b32_e32 v41, 0
	v_mov_b32_e32 v42, 0
	v_mov_b32_e32 v43, 0
	v_mov_b32_e32 v44, 0
	v_mov_b32_e32 v45, 0
	v_mov_b32_e32 v46, 0
	v_mov_b32_e32 v47, 0
	v_mov_b32_e32 v48, 0
	v_mov_b32_e32 v49, 0
	v_mov_b32_e32 v50, 0
	v_mov_b32_e32 v51, 0
	v_mov_b32_e32 v52, 0
	v_mov_b32_e32 v53, 0
	v_mov_b32_e32 v54, 0
	v_mov_b32_e32 v55, 0
	v_mov_b32_e32 v56, 0
	v_mov_b32_e32 v57, 0
	v_mov_b32_e32 v192, 0
	v_mov_b32_e32 v193, 0
	s_mov_b32 s14, 0
	s_mov_b32 s30, 0x0
	s_mov_b32 s31, 0x1a000
	s_sub_u32 s29, s13, 1
	s_waitcnt vmcnt(9)
	s_barrier
	s_cmpk_lt_u32 s15, 4
	s_cbranch_scc1 .Lmlaa_noskew
	s_barrier
.Lmlaa_noskew:
.Lmlaa_loop:
	v_add_u32_e32 v197, s30, v194
	v_add_u32_e32 v198, s30, v195
	v_add_u32_e32 v199, s30, v196
	ds_read_b128 v[90:93], v197 offset:0
	ds_read_b128 v[94:97], v197 offset:6656
	ds_read_b128 v[98:101], v197 offset:32
	ds_read_b128 v[102:105], v197 offset:6688
	ds_read_b128 v[106:109], v197 offset:64
	ds_read_b128 v[110:113], v197 offset:6720
	ds_read_b128 v[114:117], v197 offset:96
	ds_read_b128 v[118:121], v197 offset:6752
	ds_read_b128 v[122:125], v197 offset:128
	ds_read_b128 v[126:129], v197 offset:6784
	ds_read_b128 v[130:133], v197 offset:160
	ds_read_b128 v[134:137], v197 offset:6816
	s_waitcnt lgkmcnt(11)
	v_mfma_f32_32x32x16_bf16 v[58:73], v[90:93], v[2:5], 0
	ds_read_b64 v[138:139], v198 offset:0
	ds_read_b64 v[140:141], v198 offset:16
	s_waitcnt lgkmcnt(12)
	v_mfma_f32_32x32x16_bf16 v[74:89], v[94:97], v[2:5], 0
	ds_read_b64 v[142:143], v199 offset:0
	ds_read_b64 v[144:145], v199 offset:16
	s_waitcnt lgkmcnt(13)
	v_mfma_f32_32x32x16_bf16 v[58:73], v[98:101], v[6:9], v[58:73]
	ds_read_b64 v[146:147], v198 offset:32
	ds_read_b64 v[148:149], v198 offset:48
	s_waitcnt lgkmcnt(14)
	v_mfma_f32_32x32x16_bf16 v[74:89], v[102:105], v[6:9], v[74:89]
	ds_read_b64 v[150:151], v199 offset:32
	ds_read_b64 v[152:153], v199 offset:48
	s_waitcnt lgkmcnt(15)
	v_mfma_f32_32x32x16_bf16 v[58:73], v[106:109], v[10:13], v[58:73]
	ds_read_b64 v[154:155], v198 offset:64
	ds_read_b64 v[156:157], v198 offset:80
	s_waitcnt lgkmcnt(15)
	v_mfma_f32_32x32x16_bf16 v[74:89], v[110:113], v[10:13], v[74:89]
	ds_read_b64 v[158:159], v199 offset:64
	ds_read_b64 v[160:161], v199 offset:80
	s_waitcnt lgkmcnt(15)
	v_mfma_f32_32x32x16_bf16 v[58:73], v[114:117], v[14:17], v[58:73]
	ds_read_b64 v[162:163], v198 offset:96
	ds_read_b64 v[164:165], v198 offset:112
	s_waitcnt lgkmcnt(15)
	v_mfma_f32_32x32x16_bf16 v[74:89], v[118:121], v[14:17], v[74:89]
	ds_read_b64 v[166:167], v199 offset:96
	ds_read_b64 v[168:169], v199 offset:112
	s_waitcnt lgkmcnt(15)
	v_mfma_f32_32x32x16_bf16 v[58:73], v[122:125], v[18:21], v[58:73]
	s_waitcnt lgkmcnt(15)
	v_mfma_f32_32x32x16_bf16 v[74:89], v[126:129], v[18:21], v[74:89]
	s_waitcnt lgkmcnt(15)
	v_mfma_f32_32x32x16_bf16 v[58:73], v[130:133], v[22:25], v[58:73]
	s_waitcnt lgkmcnt(15)
	v_mfma_f32_32x32x16_bf16 v[74:89], v[134:137], v[22:25], v[74:89]
	s_waitcnt vmcnt(6) lgkmcnt(0)
	s_barrier
; #define LAS __attribute__((address_space(3)))
; DI unsigned pack2(float lo, float hi) { f32x2 v = {lo, hi}; bf16v2 r = __builtin_convertvector(v, bf16v2); return __builtin_bit_cast(unsigned, r); }
; DI float fexp2(float x) { return __builtin_amdgcn_exp2f(x); }
; #define MFMA32(a, b, c) __builtin_amdgcn_mfma_f32_32x32x16_bf16((a), (b), (c), 0, 0, 0)
; template <int DQK, bool MASK>
; DI void attn_tile64(const bf16x8 (&qf)[DQK / 16], f32x16& o0, f32x16& o1, float& lsum, int kbase0, int r, int h, int T, const LAS unsigned char* Ksm, const LAS unsigned char* Vsm) {
;     ...
;     bf16x8 pf[2][2];
;     f32x2 ls2 = {0.f, 0.f};
; #pragma unroll
;     for (int kt = 0; kt < 2; ++kt) {
;         float pv[16];
; #pragma unroll
;         for (int i = 0; i < 16; ++i) {
;             const float sv = sa[kt][i];
;             if (MASK) { const int kpos = kbase0 + 32 * kt + (i & 3) + 8 * (i >> 2) + 4 * h; const float e = fexp2(sv); pv[i] = kpos < T ? e : 0.f; } else pv[i] = fexp2(sv);
;         }
; #pragma unroll
;         for (int i = 0; i < 16; i += 2) ls2 = ls2 + (f32x2){pv[i], pv[i + 1]};
; #pragma unroll
;         for (int s2 = 0; s2 < 2; ++s2) {
;             u32x4 pk = {pack2(pv[8 * s2], pv[8 * s2 + 1]), pack2(pv[8 * s2 + 2], pv[8 * s2 + 3]), pack2(pv[8 * s2 + 4], pv[8 * s2 + 5]), pack2(pv[8 * s2 + 6], pv[8 * s2 + 7])};
;             pf[kt][s2] = __builtin_bit_cast(bf16x8, pk);
;         }
;     }
;     lsum += ls2[0] + ls2[1];
;     bf16x8 vf[2][2][2];
; #pragma unroll
;     for (int kt = 0; kt < 2; ++kt)
; #pragma unroll
;         for (int s2 = 0; s2 < 2; ++s2)
; #pragma unroll
;             for (int dt = 0; dt < 2; ++dt) {
;                 const u32x2 a0 = *(const LAS u32x2*)(Vsm + (32 * dt + r) * 144 + (32 * kt + 16 * s2 + 4 * h) * 2), a1 = *(const LAS u32x2*)(Vsm + (32 * dt + r) * 144 + (32 * kt + 16 * s2 + 8 + 4 * h) * 2);
;                 u32x4 av = {a0[0], a0[1], a1[0], a1[1]}; vf[kt][s2][dt] = __builtin_bit_cast(bf16x8, av);
;             }
; #pragma unroll
;     for (int kt = 0; kt < 2; ++kt)
; #pragma unroll
;         for (int s2 = 0; s2 < 2; ++s2) { o0 = MFMA32(vf[kt][s2][0], pf[kt][s2], o0); o1 = MFMA32(vf[kt][s2][1], pf[kt][s2], o1); }
	s_add_u32 m0, s31, s24
	s_nop 0
	global_load_lds_dwordx4 v[186:187], off
	v_lshl_add_u64 v[186:187], v[186:187], 0, s[36:37]
	s_add_u32 m0, s31, s25
	s_nop 0
	global_load_lds_dwordx4 v[188:189], off
	v_lshl_add_u64 v[188:189], v[188:189], 0, s[38:39]
	s_add_u32 m0, s31, s26
	s_nop 0
	global_load_lds_dwordx4 v[190:191], off
	v_lshl_add_u64 v[190:191], v[190:191], 0, s[40:41]
	s_cmp_eq_u32 s14, s29
	s_cbranch_scc1 .Lmlaa_ylast
	s_nop 15
	v_exp_f32_e32 v58, v58
	v_exp_f32_e32 v59, v59
	v_exp_f32_e32 v60, v60
	v_exp_f32_e32 v61, v61
	v_exp_f32_e32 v62, v62
	v_exp_f32_e32 v63, v63
	v_exp_f32_e32 v64, v64
	v_exp_f32_e32 v65, v65
	v_exp_f32_e32 v66, v66
	v_exp_f32_e32 v67, v67
	v_exp_f32_e32 v68, v68
	v_exp_f32_e32 v69, v69
	v_exp_f32_e32 v70, v70
	v_exp_f32_e32 v71, v71
	v_exp_f32_e32 v72, v72
	v_exp_f32_e32 v73, v73
	v_cvt_pk_bf16_f32 v170, v58, v59
	v_cvt_pk_bf16_f32 v171, v60, v61
	v_cvt_pk_bf16_f32 v172, v62, v63
	v_cvt_pk_bf16_f32 v173, v64, v65
	v_cvt_pk_bf16_f32 v174, v66, v67
	v_cvt_pk_bf16_f32 v175, v68, v69
	v_cvt_pk_bf16_f32 v176, v70, v71
	v_cvt_pk_bf16_f32 v177, v72, v73
	v_add_f32_e32 v192, v192, v58
	v_add_f32_e32 v193, v193, v59
	v_add_f32_e32 v192, v192, v60
	v_add_f32_e32 v193, v193, v61
	v_add_f32_e32 v192, v192, v62
	v_add_f32_e32 v193, v193, v63
	v_add_f32_e32 v192, v192, v64
	v_add_f32_e32 v193, v193, v65
	v_mfma_f32_32x32x16_bf16 v[26:41], v[138:141], v[170:173], v[26:41]
	v_mfma_f32_32x32x16_bf16 v[42:57], v[142:145], v[170:173], v[42:57]
	v_add_f32_e32 v192, v192, v66
	v_add_f32_e32 v193, v193, v67
	v_add_f32_e32 v192, v192, v68
	v_add_f32_e32 v193, v193, v69
	v_add_f32_e32 v192, v192, v70
	v_add_f32_e32 v193, v193, v71
	v_add_f32_e32 v192, v192, v72
	v_add_f32_e32 v193, v193, v73
	v_mfma_f32_32x32x16_bf16 v[26:41], v[146:149], v[174:177], v[26:41]
	v_mfma_f32_32x32x16_bf16 v[42:57], v[150:153], v[174:177], v[42:57]
	v_exp_f32_e32 v74, v74
	v_exp_f32_e32 v75, v75
	v_exp_f32_e32 v76, v76
	v_exp_f32_e32 v77, v77
	v_exp_f32_e32 v78, v78
	v_exp_f32_e32 v79, v79
	v_exp_f32_e32 v80, v80
	v_exp_f32_e32 v81, v81
	v_exp_f32_e32 v82, v82
	v_exp_f32_e32 v83, v83
	v_exp_f32_e32 v84, v84
	v_exp_f32_e32 v85, v85
	v_exp_f32_e32 v86, v86
	v_exp_f32_e32 v87, v87
	v_exp_f32_e32 v88, v88
	v_exp_f32_e32 v89, v89
	v_cvt_pk_bf16_f32 v178, v74, v75
	v_cvt_pk_bf16_f32 v179, v76, v77
	v_cvt_pk_bf16_f32 v180, v78, v79
	v_cvt_pk_bf16_f32 v181, v80, v81
	v_cvt_pk_bf16_f32 v182, v82, v83
	v_cvt_pk_bf16_f32 v183, v84, v85
	v_cvt_pk_bf16_f32 v184, v86, v87
	v_cvt_pk_bf16_f32 v185, v88, v89
	v_add_f32_e32 v192, v192, v74
	v_add_f32_e32 v193, v193, v75
	v_add_f32_e32 v192, v192, v76
	v_add_f32_e32 v193, v193, v77
	v_add_f32_e32 v192, v192, v78
	v_add_f32_e32 v193, v193, v79
	v_add_f32_e32 v192, v192, v80
	v_add_f32_e32 v193, v193, v81
	v_mfma_f32_32x32x16_bf16 v[26:41], v[154:157], v[178:181], v[26:41]
	v_mfma_f32_32x32x16_bf16 v[42:57], v[158:161], v[178:181], v[42:57]
	v_add_f32_e32 v192, v192, v82
	v_add_f32_e32 v193, v193, v83
	v_add_f32_e32 v192, v192, v84
	v_add_f32_e32 v193, v193, v85
	v_add_f32_e32 v192, v192, v86
	v_add_f32_e32 v193, v193, v87
	v_add_f32_e32 v192, v192, v88
	v_add_f32_e32 v193, v193, v89
	v_mfma_f32_32x32x16_bf16 v[26:41], v[162:165], v[182:185], v[26:41]
	v_mfma_f32_32x32x16_bf16 v[42:57], v[166:169], v[182:185], v[42:57]
	s_branch .Lmlaa_yend
.Lmlaa_ylast:
	s_nop 15
	v_exp_f32_e32 v58, v58
	v_exp_f32_e32 v59, v59
	v_exp_f32_e32 v60, v60
	v_exp_f32_e32 v61, v61
	v_exp_f32_e32 v62, v62
	v_exp_f32_e32 v63, v63
	v_exp_f32_e32 v64, v64
	v_exp_f32_e32 v65, v65
	v_mov_b32_e32 v66, 0
	v_mov_b32_e32 v67, 0
	v_mov_b32_e32 v68, 0
	v_mov_b32_e32 v69, 0
	v_mov_b32_e32 v70, 0
	v_mov_b32_e32 v71, 0
	v_mov_b32_e32 v72, 0
	v_mov_b32_e32 v73, 0
	v_cvt_pk_bf16_f32 v170, v58, v59
	v_cvt_pk_bf16_f32 v171, v60, v61
	v_cvt_pk_bf16_f32 v172, v62, v63
	v_cvt_pk_bf16_f32 v173, v64, v65
	v_cvt_pk_bf16_f32 v174, v66, v67
	v_cvt_pk_bf16_f32 v175, v68, v69
	v_cvt_pk_bf16_f32 v176, v70, v71
	v_cvt_pk_bf16_f32 v177, v72, v73
	v_add_f32_e32 v192, v192, v58
	v_add_f32_e32 v193, v193, v59
	v_add_f32_e32 v192, v192, v60
	v_add_f32_e32 v193, v193, v61
	v_add_f32_e32 v192, v192, v62
	v_add_f32_e32 v193, v193, v63
	v_add_f32_e32 v192, v192, v64
	v_add_f32_e32 v193, v193, v65
	v_mfma_f32_32x32x16_bf16 v[26:41], v[138:141], v[170:173], v[26:41]
	v_mfma_f32_32x32x16_bf16 v[42:57], v[142:145], v[170:173], v[42:57]
	v_add_f32_e32 v192, v192, v66
	v_add_f32_e32 v193, v193, v67
	v_add_f32_e32 v192, v192, v68
	v_add_f32_e32 v193, v193, v69
	v_add_f32_e32 v192, v192, v70
	v_add_f32_e32 v193, v193, v71
	v_add_f32_e32 v192, v192, v72
	v_add_f32_e32 v193, v193, v73
	v_mfma_f32_32x32x16_bf16 v[26:41], v[146:149], v[174:177], v[26:41]
	v_mfma_f32_32x32x16_bf16 v[42:57], v[150:153], v[174:177], v[42:57]
	v_mov_b32_e32 v74, 0
	v_mov_b32_e32 v75, 0
	v_mov_b32_e32 v76, 0
	v_mov_b32_e32 v77, 0
	v_mov_b32_e32 v78, 0
	v_mov_b32_e32 v79, 0
	v_mov_b32_e32 v80, 0
	v_mov_b32_e32 v81, 0
	v_mov_b32_e32 v82, 0
	v_mov_b32_e32 v83, 0
	v_mov_b32_e32 v84, 0
	v_mov_b32_e32 v85, 0
	v_mov_b32_e32 v86, 0
	v_mov_b32_e32 v87, 0
	v_mov_b32_e32 v88, 0
	v_mov_b32_e32 v89, 0
	s_nop 0
	v_cvt_pk_bf16_f32 v178, v74, v75
	v_cvt_pk_bf16_f32 v179, v76, v77
	v_cvt_pk_bf16_f32 v180, v78, v79
	v_cvt_pk_bf16_f32 v181, v80, v81
	v_cvt_pk_bf16_f32 v182, v82, v83
	v_cvt_pk_bf16_f32 v183, v84, v85
	v_cvt_pk_bf16_f32 v184, v86, v87
	v_cvt_pk_bf16_f32 v185, v88, v89
	v_add_f32_e32 v192, v192, v74
	v_add_f32_e32 v193, v193, v75
	v_add_f32_e32 v192, v192, v76
	v_add_f32_e32 v193, v193, v77
	v_add_f32_e32 v192, v192, v78
	v_add_f32_e32 v193, v193, v79
	v_add_f32_e32 v192, v192, v80
	v_add_f32_e32 v193, v193, v81
	v_mfma_f32_32x32x16_bf16 v[26:41], v[154:157], v[178:181], v[26:41]
	v_mfma_f32_32x32x16_bf16 v[42:57], v[158:161], v[178:181], v[42:57]
	v_add_f32_e32 v192, v192, v82
	v_add_f32_e32 v193, v193, v83
	v_add_f32_e32 v192, v192, v84
	v_add_f32_e32 v193, v193, v85
	v_add_f32_e32 v192, v192, v86
	v_add_f32_e32 v193, v193, v87
	v_add_f32_e32 v192, v192, v88
	v_add_f32_e32 v193, v193, v89
	v_mfma_f32_32x32x16_bf16 v[26:41], v[162:165], v[182:185], v[26:41]
	v_mfma_f32_32x32x16_bf16 v[42:57], v[166:169], v[182:185], v[42:57]
; DI unsigned pack2(float lo, float hi) { f32x2 v = {lo, hi}; bf16v2 r = __builtin_convertvector(v, bf16v2); return __builtin_bit_cast(unsigned, r); }
; DI float shx(float v, int lane, int o) { return __int_as_float(__builtin_amdgcn_ds_bpermute((lane ^ o) << 2, __float_as_int(v))); }
; #define ATT_GLOAD(k0_, k1_, v_, tile) do { const size_t rb = (size_t)base + (size_t)(tile) * 64; \
;         k0_ = *(const u32x4*)(K + (rb + kkey0) * ldk + koff + kpart0 * 8); \
;         if (kc1 < NKC) k1_ = *(const u32x4*)(K + (rb + kkey1) * ldk + koff + kpart1 * 8); \
;         v_ = *(const u32x4*)(Vt + (size_t)vd * MPAD + rb + vpart * 8); } while (0)
; #define ATT_LWRITE(k0_, k1_, v_, b) do { LAS unsigned char* kb = lds + (b) * ATT_BUF; \
;         *(LAS u32x4*)(kb + kkey0 * KP + kpart0 * 16) = k0_; \
;         if (kc1 < NKC) *(LAS u32x4*)(kb + kkey1 * KP + kpart1 * 16) = k1_; \
;         *(LAS u32x4*)(kb + KSZ + vd * 144 + vpart * 16) = v_; } while (0)
; template <int DQK, bool SWA>
; DI void attn_block(int wv, LAS unsigned char* lds, const bf16_t* Q, int ldq, int qoff, const bf16_t* K, int ldk, int koff, const bf16_t* Vt,
;                    int base, int T, int q0, bf16_t* O, int ldo, int ooff, const float* relb, int qhead, float sink_add) {
;     ...
;     for (int it = 0; it < ntl; it += 2) {
;         if (it + 1 < ntl) ATT_LWRITE(kB0, kB1, vB, 1);
;         if (it + 3 < ntl) ATT_GLOAD(kB0, kB1, vB, ATT_TILE(it + 3));
;         ATT_COMPUTE(it);
;         __syncthreads();
;         if (it + 1 < ntl) {
;             if (it + 2 < ntl) ATT_LWRITE(kA0, kA1, vA, 0);
;             if (it + 4 < ntl) ATT_GLOAD(kA0, kA1, vA, ATT_TILE(it + 4));
;             ATT_COMPUTE(it + 1);
;             __syncthreads();
;         }
;     }
;     ...
;     lsum += shx(lsum, lane, 32);
;     const float il = 1.f / (lsum + sink_add);
;     bf16_t* op = O + ((size_t)base + qpos) * ldo + ooff;
; #pragma unroll
;     for (int g4 = 0; g4 < 4; ++g4) {
;         u32x2 a = {pack2(o0[4 * g4] * il, o0[4 * g4 + 1] * il), pack2(o0[4 * g4 + 2] * il, o0[4 * g4 + 3] * il)};
;         u32x2 b = {pack2(o1[4 * g4] * il, o1[4 * g4 + 1] * il), pack2(o1[4 * g4 + 2] * il, o1[4 * g4 + 3] * il)};
;         *(u32x2*)(op + 8 * g4 + 4 * h) = a; *(u32x2*)(op + 32 + 8 * g4 + 4 * h) = b;
;     }
.Lmlaa_yend:
	s_barrier
	s_mov_b32 s31, s30
	s_add_u32 s30, s30, 0x5800
	s_cmp_eq_u32 s30, 0xb000
	s_cselect_b32 s30, 0xf000, s30
	s_cmp_eq_u32 s30, 0x1f800
	s_cselect_b32 s30, 0, s30
	s_add_u32 s14, s14, 1
	s_cmp_lt_u32 s14, s13
	s_cbranch_scc1 .Lmlaa_loop
	s_waitcnt vmcnt(0)
	s_cmpk_gt_u32 s15, 3
	s_cbranch_scc1 .Lmlaa_noskew2
	s_barrier
.Lmlaa_noskew2:
	s_nop 15
	v_add_f32_e32 v192, v192, v193
	v_xor_b32_e32 v197, 32, v254
	v_lshlrev_b32_e32 v197, 2, v197
	s_nop 0
	ds_bpermute_b32 v198, v197, v192
	s_waitcnt lgkmcnt(0)
	v_add_f32_e32 v192, v192, v198
	v_rcp_f32_e32 v192, v192
	s_nop 0
	v_mul_f32_e32 v26, v26, v192
	v_mul_f32_e32 v27, v27, v192
	v_mul_f32_e32 v28, v28, v192
	v_mul_f32_e32 v29, v29, v192
	v_mul_f32_e32 v30, v30, v192
	v_mul_f32_e32 v31, v31, v192
	v_mul_f32_e32 v32, v32, v192
	v_mul_f32_e32 v33, v33, v192
	v_mul_f32_e32 v34, v34, v192
	v_mul_f32_e32 v35, v35, v192
	v_mul_f32_e32 v36, v36, v192
	v_mul_f32_e32 v37, v37, v192
	v_mul_f32_e32 v38, v38, v192
	v_mul_f32_e32 v39, v39, v192
	v_mul_f32_e32 v40, v40, v192
	v_mul_f32_e32 v41, v41, v192
	v_mul_f32_e32 v42, v42, v192
	v_mul_f32_e32 v43, v43, v192
	v_mul_f32_e32 v44, v44, v192
	v_mul_f32_e32 v45, v45, v192
	v_mul_f32_e32 v46, v46, v192
	v_mul_f32_e32 v47, v47, v192
	v_mul_f32_e32 v48, v48, v192
	v_mul_f32_e32 v49, v49, v192
	v_mul_f32_e32 v50, v50, v192
	v_mul_f32_e32 v51, v51, v192
	v_mul_f32_e32 v52, v52, v192
	v_mul_f32_e32 v53, v53, v192
	v_mul_f32_e32 v54, v54, v192
	v_mul_f32_e32 v55, v55, v192
	v_mul_f32_e32 v56, v56, v192
	v_mul_f32_e32 v57, v57, v192
	v_cvt_pk_bf16_f32 v58, v26, v27
	v_cvt_pk_bf16_f32 v59, v28, v29
	v_cvt_pk_bf16_f32 v60, v42, v43
	v_cvt_pk_bf16_f32 v61, v44, v45
	v_cvt_pk_bf16_f32 v62, v30, v31
	v_cvt_pk_bf16_f32 v63, v32, v33
	v_cvt_pk_bf16_f32 v64, v46, v47
	v_cvt_pk_bf16_f32 v65, v48, v49
	v_cvt_pk_bf16_f32 v66, v34, v35
	v_cvt_pk_bf16_f32 v67, v36, v37
	v_cvt_pk_bf16_f32 v68, v50, v51
	v_cvt_pk_bf16_f32 v69, v52, v53
	v_cvt_pk_bf16_f32 v70, v38, v39
	v_cvt_pk_bf16_f32 v71, v40, v41
	v_cvt_pk_bf16_f32 v72, v54, v55
	v_cvt_pk_bf16_f32 v73, v56, v57
	global_store_dwordx2 v200, v[58:59], s[22:23] offset:0
	global_store_dwordx2 v200, v[60:61], s[22:23] offset:64
	global_store_dwordx2 v200, v[62:63], s[22:23] offset:16
	global_store_dwordx2 v200, v[64:65], s[22:23] offset:80
	global_store_dwordx2 v200, v[66:67], s[22:23] offset:32
	global_store_dwordx2 v200, v[68:69], s[22:23] offset:96
	global_store_dwordx2 v200, v[70:71], s[22:23] offset:48
	global_store_dwordx2 v200, v[72:73], s[22:23] offset:112
	v_readlane_b32 s4, v255, 17
	v_readlane_b32 s5, v255, 18
	v_readlane_b32 s6, v255, 19
	v_readlane_b32 s7, v255, 20
	v_readlane_b32 s8, v255, 21
	v_readlane_b32 s9, v255, 22
	v_readlane_b32 s10, v255, 23
	v_readlane_b32 s11, v255, 24
	v_readlane_b32 s12, v255, 25
	v_readlane_b32 s13, v255, 26
	v_readlane_b32 s14, v255, 27
	v_readlane_b32 s15, v255, 28
	v_readlane_b32 s16, v255, 29
	v_readlane_b32 s17, v255, 30
	v_readlane_b32 s18, v255, 31
	v_readlane_b32 s19, v255, 32
	v_readlane_b32 s20, v255, 33
	v_readlane_b32 s21, v255, 34
	v_readlane_b32 s22, v255, 35
	v_readlane_b32 s23, v255, 36
	v_readlane_b32 s24, v255, 37
	v_readlane_b32 s25, v255, 38
	v_readlane_b32 s26, v255, 39
	v_readlane_b32 s27, v255, 40
	v_readlane_b32 s28, v255, 41
	v_readlane_b32 s29, v255, 42
	v_readlane_b32 s30, v255, 43
	v_readlane_b32 s31, v255, 44
	v_readlane_b32 s36, v255, 45
	v_readlane_b32 s37, v255, 46
	v_readlane_b32 s38, v255, 47
	v_readlane_b32 s39, v255, 48
	v_readlane_b32 s40, v255, 49
	v_readlane_b32 s41, v255, 50
	v_readlane_b32 s42, v255, 51
	v_readlane_b32 s43, v255, 52
	v_readlane_b32 s44, v255, 53
	v_readlane_b32 s45, v255, 54
	v_readlane_b32 s46, v255, 55
	v_readlane_b32 s47, v255, 56
	v_readlane_b32 s48, v255, 57
	v_readlane_b32 s49, v255, 58
	v_readlane_b32 s50, v255, 59
	v_readlane_b32 s51, v255, 60
	s_nop 4
	s_branch .LBB0_1237

; DI unsigned pack2(float lo, float hi) { f32x2 v = {lo, hi}; bf16v2 r = __builtin_convertvector(v, bf16v2); return __builtin_bit_cast(unsigned, r); }
; DI float fexp2(float x) { return __builtin_amdgcn_exp2f(x); }
; DI float shx(float v, int lane, int o) { return __int_as_float(__builtin_amdgcn_ds_bpermute((lane ^ o) << 2, __float_as_int(v))); }
; template <int DQK, bool SWA, bool MASK, class KF, class VF>
; DI void attn_subtile(const bf16x8 (&qf)[DQK / 16], f32x16& o0, f32x16& o1, float& lsum, int kbase, int h, int qpos, int T, const LAS float* LUT, KF kfrag, VF vfrag) {
;     ...
;         for (int i = 0; i < 16; ++i) {
;             const int kpos = kbase + (i & 3) + 8 * (i >> 2) + 4 * h, rel = kpos - qpos;
;             const float e = fexp2(s[i] + bias[i]);
;             const bool vis = kpos < T && (kpos < 16 || (rel <= 128 && rel >= -128));
;             pv[i] = vis ? e : 0.f; lsum += pv[i];
;         }
; template <int DQK, bool SWA>
; DI void attn_block(int wv, LAS unsigned char* lds, const bf16_t* Q, int ldq, int qoff, const bf16_t* K, int ldk, int koff, const bf16_t* Vt,
;                    int base, int T, int q0, bf16_t* O, int ldo, int ooff, const float* relb, int qhead, float sink_add) {
;     ...
;     lsum += shx(lsum, lane, 32);
;     const float il = 1.f / (lsum + sink_add);
;     bf16_t* op = O + ((size_t)base + qpos) * ldo + ooff;
; #pragma unroll
;     for (int g4 = 0; g4 < 4; ++g4) {
;         u32x2 a = {pack2(o0[4 * g4] * il, o0[4 * g4 + 1] * il), pack2(o0[4 * g4 + 2] * il, o0[4 * g4 + 3] * il)};
;         u32x2 b = {pack2(o1[4 * g4] * il, o1[4 * g4 + 1] * il), pack2(o1[4 * g4 + 2] * il, o1[4 * g4 + 3] * il)};
;         *(u32x2*)(op + 8 * g4 + 4 * h) = a; *(u32x2*)(op + 32 + 8 * g4 + 4 * h) = b;
;     }
.LBB0_1215:
	s_or_b64 exec, exec, s[84:85]
	v_or_b32_e32 v41, 16, v102
	v_cmp_gt_i32_e64 s[6:7], s90, v41
	s_and_saveexec_b64 s[84:85], s[6:7]
	s_cbranch_execz .LBB0_1180
	s_waitcnt lgkmcnt(7)
	v_add_f32_e32 v39, v136, v42
	v_exp_f32_e32 v39, v39
	v_sub_u32_e32 v41, v41, v107
	v_add_u32_e32 v41, 0x80, v41
	v_cmp_lt_u32_e64 s[6:7], s10, v104
	v_cmp_gt_u32_e64 s[12:13], s9, v41
	s_or_b64 s[6:7], s[6:7], s[12:13]
	v_cndmask_b32_e64 v39, 0, v39, s[6:7]
	s_branch .LBB0_1180
.LBB0_1218:
	s_or_b64 exec, exec, s[82:83]

; DI void phase_queue(int wv, const Params& p, int l, LAS unsigned char* lds) {
;     ...
;         if (it < N_MLA) {
;             int seq, head, qb;
;             if (it < 256) { seq = 0; head = it & 3; qb = it >> 2; } else { const int m = it - 256; seq = 1 + (m >> 5); head = m & 3; qb = (m >> 2) & 7; }
;             attn_block<96, false>(wv, lds, QM, 384, head * 96, KM, 384, head * 96, VTM + (size_t)head * 64 * MPAD, seq_start(seq), seq_len(seq), qb * 256, MIX, 1024, 768 + head * 64, nullptr, 0, 0.f);
.LBB0_2759:
	s_and_b64 vcc, exec, s[4:5]
	s_cbranch_vccz .LBB0_2804
	v_writelane_b32 v255, s4, 17
	v_writelane_b32 v255, s5, 18
	v_writelane_b32 v255, s6, 19
	v_writelane_b32 v255, s7, 20
	v_writelane_b32 v255, s8, 21
	v_writelane_b32 v255, s9, 22
	v_writelane_b32 v255, s10, 23
	v_writelane_b32 v255, s11, 24
	v_writelane_b32 v255, s12, 25
	v_writelane_b32 v255, s13, 26
	v_writelane_b32 v255, s14, 27
	v_writelane_b32 v255, s15, 28
	v_writelane_b32 v255, s16, 29
	v_writelane_b32 v255, s17, 30
	v_writelane_b32 v255, s18, 31
	v_writelane_b32 v255, s19, 32
	v_writelane_b32 v255, s20, 33
	v_writelane_b32 v255, s21, 34
	v_writelane_b32 v255, s22, 35
	v_writelane_b32 v255, s23, 36
	v_writelane_b32 v255, s24, 37
	v_writelane_b32 v255, s25, 38
	v_writelane_b32 v255, s26, 39
	v_writelane_b32 v255, s27, 40
	v_writelane_b32 v255, s28, 41
	v_writelane_b32 v255, s29, 42
	v_writelane_b32 v255, s30, 43
	v_writelane_b32 v255, s31, 44
	v_writelane_b32 v255, s36, 45
	v_writelane_b32 v255, s37, 46
	v_writelane_b32 v255, s38, 47
	v_writelane_b32 v255, s39, 48
	v_writelane_b32 v255, s40, 49
	v_writelane_b32 v255, s41, 50
	v_writelane_b32 v255, s42, 51
	v_writelane_b32 v255, s43, 52
	v_writelane_b32 v255, s44, 53
	v_writelane_b32 v255, s45, 54
	v_writelane_b32 v255, s46, 55
	v_writelane_b32 v255, s47, 56
	v_writelane_b32 v255, s48, 57
	v_writelane_b32 v255, s49, 58
	v_writelane_b32 v255, s50, 59
	v_writelane_b32 v255, s51, 60
	s_sub_u32 s4, s87, 0x294
	s_cmpk_lt_u32 s4, 0x100
	s_cbranch_scc1 .Lmlab_seq0
	s_sub_u32 s5, s4, 0x100
	s_lshr_b32 s9, s5, 5
	s_add_u32 s9, s9, 1
	s_and_b32 s8, s5, 3
	s_bfe_u32 s10, s5, 0x30002
	s_mul_i32 s11, s9, 0x810
	s_add_u32 s11, s11, 0x3800
	s_movk_i32 s13, 33
	s_branch .Lmlab_dec

; DI unsigned pack2(float lo, float hi) { f32x2 v = {lo, hi}; bf16v2 r = __builtin_convertvector(v, bf16v2); return __builtin_bit_cast(unsigned, r); }
; DI float fexp2(float x) { return __builtin_amdgcn_exp2f(x); }
; DI float shx(float v, int lane, int o) { return __int_as_float(__builtin_amdgcn_ds_bpermute((lane ^ o) << 2, __float_as_int(v))); }
; template <int DQK, bool SWA, bool MASK, class KF, class VF>
; DI void attn_subtile(const bf16x8 (&qf)[DQK / 16], f32x16& o0, f32x16& o1, float& lsum, int kbase, int h, int qpos, int T, const LAS float* LUT, KF kfrag, VF vfrag) {
;     ...
;         for (int i = 0; i < 16; ++i) {
;             const int kpos = kbase + (i & 3) + 8 * (i >> 2) + 4 * h, rel = kpos - qpos;
;             const float e = fexp2(s[i] + bias[i]);
;             const bool vis = kpos < T && (kpos < 16 || (rel <= 128 && rel >= -128));
;             pv[i] = vis ? e : 0.f; lsum += pv[i];
;         }
; template <int DQK, bool SWA>
; DI void attn_block(int wv, LAS unsigned char* lds, const bf16_t* Q, int ldq, int qoff, const bf16_t* K, int ldk, int koff, const bf16_t* Vt,
;                    int base, int T, int q0, bf16_t* O, int ldo, int ooff, const float* relb, int qhead, float sink_add) {
;     ...
;     lsum += shx(lsum, lane, 32);
;     const float il = 1.f / (lsum + sink_add);
;     bf16_t* op = O + ((size_t)base + qpos) * ldo + ooff;
; #pragma unroll
;     for (int g4 = 0; g4 < 4; ++g4) {
;         u32x2 a = {pack2(o0[4 * g4] * il, o0[4 * g4 + 1] * il), pack2(o0[4 * g4 + 2] * il, o0[4 * g4 + 3] * il)};
;         u32x2 b = {pack2(o1[4 * g4] * il, o1[4 * g4 + 1] * il), pack2(o1[4 * g4 + 2] * il, o1[4 * g4 + 3] * il)};
;         *(u32x2*)(op + 8 * g4 + 4 * h) = a; *(u32x2*)(op + 32 + 8 * g4 + 4 * h) = b;
;     }
.LBB0_2849:
	s_or_b64 exec, exec, s[68:69]
	v_or_b32_e32 v41, 16, v102
	v_cmp_gt_i32_e64 s[4:5], s88, v41
	s_and_saveexec_b64 s[68:69], s[4:5]
	s_cbranch_execz .LBB0_2814
	s_waitcnt lgkmcnt(7)
	v_add_f32_e32 v39, v136, v42
	v_exp_f32_e32 v39, v39
	v_sub_u32_e32 v41, v41, v108
	v_add_u32_e32 v41, 0x80, v41
	v_cmp_lt_u32_e64 s[4:5], s80, v104
	v_cmp_gt_u32_e64 s[8:9], s79, v41
	s_or_b64 s[4:5], s[4:5], s[8:9]
	v_cndmask_b32_e64 v39, 0, v39, s[4:5]
	s_branch .LBB0_2814
.LBB0_2852:
	s_or_b64 exec, exec, s[66:67]
